# v088 + adaLN GEMV loop loads 4 k-steps (32 weight rows) per trip before consuming them (4x memory-level parallelism)
# speedup vs baseline: 1.0111x; 1.0067x over previous
.LBB0_34:
	s_mov_b32 s46, 0xfffb8000
	v_add_co_u32_e64 v24, s[46:47], s46, v10
	v_add_co_u32_e32 v22, vcc, 0xfffac000, v10
	s_nop 0
	v_addc_co_u32_e64 v25, s[46:47], -1, v11, s[46:47]
	s_mov_b32 s46, 0xfffc4000
	s_nop 0
	v_add_co_u32_e64 v26, s[46:47], s46, v10
	v_addc_co_u32_e32 v23, vcc, -1, v11, vcc
	s_nop 0
	v_addc_co_u32_e64 v27, s[46:47], -1, v11, s[46:47]
	s_mov_b32 s46, 0xfffd0000
	s_nop 0
	v_add_co_u32_e64 v28, s[46:47], s46, v10
	s_nop 1
	v_addc_co_u32_e64 v29, s[46:47], -1, v11, s[46:47]
	s_mov_b32 s46, 0xfffdc000
	s_nop 0
	v_add_co_u32_e64 v30, s[46:47], s46, v10
	s_nop 1
	v_addc_co_u32_e64 v31, s[46:47], -1, v11, s[46:47]
	s_mov_b32 s46, 0xfffe8000
	s_nop 0
	v_add_co_u32_e64 v32, s[46:47], s46, v10
	s_nop 1
	v_addc_co_u32_e64 v33, s[46:47], -1, v11, s[46:47]
	s_mov_b32 s46, 0xffff4000
	s_nop 0
	v_add_co_u32_e64 v34, s[46:47], s46, v10
	s_nop 1
	v_addc_co_u32_e64 v35, s[46:47], -1, v11, s[46:47]
	global_load_dword v62, v[24:25], off nt
	global_load_dword v64, v[26:27], off nt
	global_load_dword v66, v[28:29], off nt
	global_load_dword v68, v[30:31], off nt
	global_load_dword v70, v[22:23], off nt
	global_load_dword v72, v[32:33], off nt
	global_load_dword v74, v[34:35], off nt
	global_load_dword v76, v[10:11], off nt
	s_mov_b64 s[46:47], 0x60000
	v_lshl_add_u64 v[130:131], v[10:11], 0, s[46:47]
	s_mov_b32 s46, 0xfffb8000
	v_add_co_u32_e64 v24, s[46:47], s46, v130
	v_add_co_u32_e32 v22, vcc, 0xfffac000, v130
	s_nop 0
	v_addc_co_u32_e64 v25, s[46:47], -1, v131, s[46:47]
	s_mov_b32 s46, 0xfffc4000
	s_nop 0
	v_add_co_u32_e64 v26, s[46:47], s46, v130
	v_addc_co_u32_e32 v23, vcc, -1, v131, vcc
	s_nop 0
	v_addc_co_u32_e64 v27, s[46:47], -1, v131, s[46:47]
	s_mov_b32 s46, 0xfffd0000
	s_nop 0
	v_add_co_u32_e64 v28, s[46:47], s46, v130
	s_nop 1
	v_addc_co_u32_e64 v29, s[46:47], -1, v131, s[46:47]
	s_mov_b32 s46, 0xfffdc000
	s_nop 0
	v_add_co_u32_e64 v30, s[46:47], s46, v130
	s_nop 1
	v_addc_co_u32_e64 v31, s[46:47], -1, v131, s[46:47]
	s_mov_b32 s46, 0xfffe8000
	s_nop 0
	v_add_co_u32_e64 v32, s[46:47], s46, v130
	s_nop 1
	v_addc_co_u32_e64 v33, s[46:47], -1, v131, s[46:47]
	s_mov_b32 s46, 0xffff4000
	s_nop 0
	v_add_co_u32_e64 v34, s[46:47], s46, v130
	s_nop 1
	v_addc_co_u32_e64 v35, s[46:47], -1, v131, s[46:47]
	global_load_dword v82, v[24:25], off nt
	global_load_dword v84, v[26:27], off nt
	global_load_dword v86, v[28:29], off nt
	global_load_dword v88, v[30:31], off nt
	global_load_dword v90, v[22:23], off nt
	global_load_dword v92, v[32:33], off nt
	global_load_dword v94, v[34:35], off nt
	global_load_dword v96, v[130:131], off nt
	s_mov_b64 s[46:47], 0x60000
	v_lshl_add_u64 v[130:131], v[130:131], 0, s[46:47]
	s_mov_b32 s46, 0xfffb8000
	v_add_co_u32_e64 v24, s[46:47], s46, v130
	v_add_co_u32_e32 v22, vcc, 0xfffac000, v130
	s_nop 0
	v_addc_co_u32_e64 v25, s[46:47], -1, v131, s[46:47]
	s_mov_b32 s46, 0xfffc4000
	s_nop 0
	v_add_co_u32_e64 v26, s[46:47], s46, v130
	v_addc_co_u32_e32 v23, vcc, -1, v131, vcc
	s_nop 0
	v_addc_co_u32_e64 v27, s[46:47], -1, v131, s[46:47]
	s_mov_b32 s46, 0xfffd0000
	s_nop 0
	v_add_co_u32_e64 v28, s[46:47], s46, v130
	s_nop 1
	v_addc_co_u32_e64 v29, s[46:47], -1, v131, s[46:47]
	s_mov_b32 s46, 0xfffdc000
	s_nop 0
	v_add_co_u32_e64 v30, s[46:47], s46, v130
	s_nop 1
	v_addc_co_u32_e64 v31, s[46:47], -1, v131, s[46:47]
	s_mov_b32 s46, 0xfffe8000
	s_nop 0
	v_add_co_u32_e64 v32, s[46:47], s46, v130
	s_nop 1
	v_addc_co_u32_e64 v33, s[46:47], -1, v131, s[46:47]
	s_mov_b32 s46, 0xffff4000
	s_nop 0
	v_add_co_u32_e64 v34, s[46:47], s46, v130
	s_nop 1
	v_addc_co_u32_e64 v35, s[46:47], -1, v131, s[46:47]
	global_load_dword v98, v[24:25], off nt
	global_load_dword v100, v[26:27], off nt
	global_load_dword v102, v[28:29], off nt
	global_load_dword v104, v[30:31], off nt
	global_load_dword v106, v[22:23], off nt
	global_load_dword v108, v[32:33], off nt
	global_load_dword v110, v[34:35], off nt
	global_load_dword v112, v[130:131], off nt
	s_mov_b64 s[46:47], 0x60000
	v_lshl_add_u64 v[130:131], v[130:131], 0, s[46:47]
	s_mov_b32 s46, 0xfffb8000
	v_add_co_u32_e64 v24, s[46:47], s46, v130
	v_add_co_u32_e32 v22, vcc, 0xfffac000, v130
	s_nop 0
	v_addc_co_u32_e64 v25, s[46:47], -1, v131, s[46:47]
	s_mov_b32 s46, 0xfffc4000
	s_nop 0
	v_add_co_u32_e64 v26, s[46:47], s46, v130
	v_addc_co_u32_e32 v23, vcc, -1, v131, vcc
	s_nop 0
	v_addc_co_u32_e64 v27, s[46:47], -1, v131, s[46:47]
	s_mov_b32 s46, 0xfffd0000
	s_nop 0
	v_add_co_u32_e64 v28, s[46:47], s46, v130
	s_nop 1
	v_addc_co_u32_e64 v29, s[46:47], -1, v131, s[46:47]
	s_mov_b32 s46, 0xfffdc000
	s_nop 0
	v_add_co_u32_e64 v30, s[46:47], s46, v130
	s_nop 1
	v_addc_co_u32_e64 v31, s[46:47], -1, v131, s[46:47]
	s_mov_b32 s46, 0xfffe8000
	s_nop 0
	v_add_co_u32_e64 v32, s[46:47], s46, v130
	s_nop 1
	v_addc_co_u32_e64 v33, s[46:47], -1, v131, s[46:47]
	s_mov_b32 s46, 0xffff4000
	s_nop 0
	v_add_co_u32_e64 v34, s[46:47], s46, v130
	s_nop 1
	v_addc_co_u32_e64 v35, s[46:47], -1, v131, s[46:47]
	global_load_dword v114, v[24:25], off nt
	global_load_dword v116, v[26:27], off nt
	global_load_dword v118, v[28:29], off nt
	global_load_dword v120, v[30:31], off nt
	global_load_dword v122, v[22:23], off nt
	global_load_dword v124, v[32:33], off nt
	global_load_dword v126, v[34:35], off nt
	global_load_dword v128, v[130:131], off nt
	s_add_i32 s46, s2, s0
	v_mov_b32_e32 v50, s46
	s_add_i32 s49, s46, 0x10800
	s_add_i32 s50, s46, 0x10810
	ds_read_b128 v[22:25], v50 offset:2048
	ds_read_b128 v[26:29], v50 offset:2064
	v_mov_b32_e32 v54, s49
	ds_read_b128 v[30:33], v50 offset:18432
	ds_read_b128 v[34:37], v50 offset:18448
	ds_read_b128 v[38:41], v50 offset:34816
	ds_read_b128 v[42:45], v50 offset:34832
	ds_read_b128 v[46:49], v50 offset:51200
	ds_read_b128 v[50:53], v50 offset:51216
	v_mov_b32_e32 v58, s50
	ds_read_b128 v[54:57], v54
	ds_read_b128 v[58:61], v58
	s_waitcnt lgkmcnt(9)
	v_mov_b32_e32 v78, v22
	s_waitcnt lgkmcnt(7)
	v_mov_b32_e32 v79, v30
	s_waitcnt lgkmcnt(5)
	v_mov_b32_e32 v80, v38
	s_waitcnt lgkmcnt(3)
	v_mov_b32_e32 v81, v46
	v_mov_b32_e32 v30, v23
	v_mov_b32_e32 v46, v39
	v_mov_b32_e32 v22, v24
	v_mov_b32_e32 v23, v32
	v_mov_b32_e32 v38, v40
	v_mov_b32_e32 v39, v48
	v_mov_b32_e32 v32, v25
	v_mov_b32_e32 v48, v41
	v_mov_b32_e32 v24, v26
	v_mov_b32_e32 v25, v34
	v_mov_b32_e32 v40, v42
	s_waitcnt lgkmcnt(2)
	v_mov_b32_e32 v41, v50
	v_mov_b32_e32 v34, v27
	v_mov_b32_e32 v50, v43
	v_mov_b32_e32 v26, v28
	v_mov_b32_e32 v27, v36
	v_mov_b32_e32 v42, v44
	v_mov_b32_e32 v43, v52
	s_add_i32 s0, s0, 32
	s_mov_b64 s[46:47], 0x60000
	v_mov_b32_e32 v36, v29
	v_mov_b32_e32 v52, v45
	v_lshl_add_u64 v[10:11], v[10:11], 0, s[46:47]
	s_cmp_eq_u32 s0, 0
	s_waitcnt vmcnt(27)
	v_pk_fma_f32 v[12:13], v[70:71], v[78:79], v[12:13] op_sel_hi:[0,1,1]
	v_pk_fma_f32 v[14:15], v[70:71], v[80:81], v[14:15] op_sel_hi:[0,1,1]
	s_waitcnt lgkmcnt(1)
	v_fmac_f32_e32 v21, v70, v54
	v_pk_fma_f32 v[12:13], v[62:63], v[30:31], v[12:13] op_sel_hi:[0,1,1]
	v_pk_fma_f32 v[14:15], v[62:63], v[46:47], v[14:15] op_sel_hi:[0,1,1]
	v_fmac_f32_e32 v21, v62, v55
	v_pk_fma_f32 v[12:13], v[64:65], v[22:23], v[12:13] op_sel_hi:[0,1,1]
	v_pk_fma_f32 v[14:15], v[64:65], v[38:39], v[14:15] op_sel_hi:[0,1,1]
	v_fmac_f32_e32 v21, v64, v56
	v_pk_fma_f32 v[12:13], v[66:67], v[32:33], v[12:13] op_sel_hi:[0,1,1]
	v_pk_fma_f32 v[14:15], v[66:67], v[48:49], v[14:15] op_sel_hi:[0,1,1]
	v_fmac_f32_e32 v21, v66, v57
	v_pk_fma_f32 v[12:13], v[68:69], v[24:25], v[12:13] op_sel_hi:[0,1,1]
	v_pk_fma_f32 v[14:15], v[68:69], v[40:41], v[14:15] op_sel_hi:[0,1,1]
	s_waitcnt lgkmcnt(0)
	v_fmac_f32_e32 v21, v68, v58
	s_waitcnt vmcnt(26)
	v_pk_fma_f32 v[12:13], v[72:73], v[34:35], v[12:13] op_sel_hi:[0,1,1]
	v_pk_fma_f32 v[14:15], v[72:73], v[50:51], v[14:15] op_sel_hi:[0,1,1]
	v_fmac_f32_e32 v21, v72, v59
	s_waitcnt vmcnt(25)
	v_pk_fma_f32 v[12:13], v[74:75], v[26:27], v[12:13] op_sel_hi:[0,1,1]
	v_pk_fma_f32 v[14:15], v[74:75], v[42:43], v[14:15] op_sel_hi:[0,1,1]
	v_fmac_f32_e32 v21, v74, v60
	s_waitcnt vmcnt(24)
	v_pk_fma_f32 v[12:13], v[76:77], v[36:37], v[12:13] op_sel_hi:[0,1,1]
	v_pk_fma_f32 v[14:15], v[76:77], v[52:53], v[14:15] op_sel_hi:[0,1,1]
	v_fmac_f32_e32 v21, v76, v61
	s_add_i32 s46, s2, s0
	v_mov_b32_e32 v50, s46
	s_add_i32 s49, s46, 0x10800
	s_add_i32 s50, s46, 0x10810
	ds_read_b128 v[22:25], v50 offset:2048
	ds_read_b128 v[26:29], v50 offset:2064
	v_mov_b32_e32 v54, s49
	ds_read_b128 v[30:33], v50 offset:18432
	ds_read_b128 v[34:37], v50 offset:18448
	ds_read_b128 v[38:41], v50 offset:34816
	ds_read_b128 v[42:45], v50 offset:34832
	ds_read_b128 v[46:49], v50 offset:51200
	ds_read_b128 v[50:53], v50 offset:51216
	v_mov_b32_e32 v58, s50
	ds_read_b128 v[54:57], v54
	ds_read_b128 v[58:61], v58
	s_waitcnt lgkmcnt(9)
	v_mov_b32_e32 v78, v22
	s_waitcnt lgkmcnt(7)
	v_mov_b32_e32 v79, v30
	s_waitcnt lgkmcnt(5)
	v_mov_b32_e32 v80, v38
	s_waitcnt lgkmcnt(3)
	v_mov_b32_e32 v81, v46
	v_mov_b32_e32 v30, v23
	v_mov_b32_e32 v46, v39
	v_mov_b32_e32 v22, v24
	v_mov_b32_e32 v23, v32
	v_mov_b32_e32 v38, v40
	v_mov_b32_e32 v39, v48
	v_mov_b32_e32 v32, v25
	v_mov_b32_e32 v48, v41
	v_mov_b32_e32 v24, v26
	v_mov_b32_e32 v25, v34
	v_mov_b32_e32 v40, v42
	s_waitcnt lgkmcnt(2)
	v_mov_b32_e32 v41, v50
	v_mov_b32_e32 v34, v27
	v_mov_b32_e32 v50, v43
	v_mov_b32_e32 v26, v28
	v_mov_b32_e32 v27, v36
	v_mov_b32_e32 v42, v44
	v_mov_b32_e32 v43, v52
	s_add_i32 s0, s0, 32
	s_mov_b64 s[46:47], 0x60000
	v_mov_b32_e32 v36, v29
	v_mov_b32_e32 v52, v45
	v_lshl_add_u64 v[10:11], v[10:11], 0, s[46:47]
	s_cmp_eq_u32 s0, 0
	s_waitcnt vmcnt(19)
	v_pk_fma_f32 v[12:13], v[90:91], v[78:79], v[12:13] op_sel_hi:[0,1,1]
	v_pk_fma_f32 v[14:15], v[90:91], v[80:81], v[14:15] op_sel_hi:[0,1,1]
	s_waitcnt lgkmcnt(1)
	v_fmac_f32_e32 v21, v90, v54
	v_pk_fma_f32 v[12:13], v[82:83], v[30:31], v[12:13] op_sel_hi:[0,1,1]
	v_pk_fma_f32 v[14:15], v[82:83], v[46:47], v[14:15] op_sel_hi:[0,1,1]
	v_fmac_f32_e32 v21, v82, v55
	v_pk_fma_f32 v[12:13], v[84:85], v[22:23], v[12:13] op_sel_hi:[0,1,1]
	v_pk_fma_f32 v[14:15], v[84:85], v[38:39], v[14:15] op_sel_hi:[0,1,1]
	v_fmac_f32_e32 v21, v84, v56
	v_pk_fma_f32 v[12:13], v[86:87], v[32:33], v[12:13] op_sel_hi:[0,1,1]
	v_pk_fma_f32 v[14:15], v[86:87], v[48:49], v[14:15] op_sel_hi:[0,1,1]
	v_fmac_f32_e32 v21, v86, v57
	v_pk_fma_f32 v[12:13], v[88:89], v[24:25], v[12:13] op_sel_hi:[0,1,1]
	v_pk_fma_f32 v[14:15], v[88:89], v[40:41], v[14:15] op_sel_hi:[0,1,1]
	s_waitcnt lgkmcnt(0)
	v_fmac_f32_e32 v21, v88, v58
	s_waitcnt vmcnt(18)
	v_pk_fma_f32 v[12:13], v[92:93], v[34:35], v[12:13] op_sel_hi:[0,1,1]
	v_pk_fma_f32 v[14:15], v[92:93], v[50:51], v[14:15] op_sel_hi:[0,1,1]
	v_fmac_f32_e32 v21, v92, v59
	s_waitcnt vmcnt(17)
	v_pk_fma_f32 v[12:13], v[94:95], v[26:27], v[12:13] op_sel_hi:[0,1,1]
	v_pk_fma_f32 v[14:15], v[94:95], v[42:43], v[14:15] op_sel_hi:[0,1,1]
	v_fmac_f32_e32 v21, v94, v60
	s_waitcnt vmcnt(16)
	v_pk_fma_f32 v[12:13], v[96:97], v[36:37], v[12:13] op_sel_hi:[0,1,1]
	v_pk_fma_f32 v[14:15], v[96:97], v[52:53], v[14:15] op_sel_hi:[0,1,1]
	v_fmac_f32_e32 v21, v96, v61
	s_add_i32 s46, s2, s0
	v_mov_b32_e32 v50, s46
	s_add_i32 s49, s46, 0x10800
	s_add_i32 s50, s46, 0x10810
	ds_read_b128 v[22:25], v50 offset:2048
	ds_read_b128 v[26:29], v50 offset:2064
	v_mov_b32_e32 v54, s49
	ds_read_b128 v[30:33], v50 offset:18432
	ds_read_b128 v[34:37], v50 offset:18448
	ds_read_b128 v[38:41], v50 offset:34816
	ds_read_b128 v[42:45], v50 offset:34832
	ds_read_b128 v[46:49], v50 offset:51200
	ds_read_b128 v[50:53], v50 offset:51216
	v_mov_b32_e32 v58, s50
	ds_read_b128 v[54:57], v54
	ds_read_b128 v[58:61], v58
	s_waitcnt lgkmcnt(9)
	v_mov_b32_e32 v78, v22
	s_waitcnt lgkmcnt(7)
	v_mov_b32_e32 v79, v30
	s_waitcnt lgkmcnt(5)
	v_mov_b32_e32 v80, v38
	s_waitcnt lgkmcnt(3)
	v_mov_b32_e32 v81, v46
	v_mov_b32_e32 v30, v23
	v_mov_b32_e32 v46, v39
	v_mov_b32_e32 v22, v24
	v_mov_b32_e32 v23, v32
	v_mov_b32_e32 v38, v40
	v_mov_b32_e32 v39, v48
	v_mov_b32_e32 v32, v25
	v_mov_b32_e32 v48, v41
	v_mov_b32_e32 v24, v26
	v_mov_b32_e32 v25, v34
	v_mov_b32_e32 v40, v42
	s_waitcnt lgkmcnt(2)
	v_mov_b32_e32 v41, v50
	v_mov_b32_e32 v34, v27
	v_mov_b32_e32 v50, v43
	v_mov_b32_e32 v26, v28
	v_mov_b32_e32 v27, v36
	v_mov_b32_e32 v42, v44
	v_mov_b32_e32 v43, v52
	s_add_i32 s0, s0, 32
	s_mov_b64 s[46:47], 0x60000
	v_mov_b32_e32 v36, v29
	v_mov_b32_e32 v52, v45
	v_lshl_add_u64 v[10:11], v[10:11], 0, s[46:47]
	s_cmp_eq_u32 s0, 0
	s_waitcnt vmcnt(11)
	v_pk_fma_f32 v[12:13], v[106:107], v[78:79], v[12:13] op_sel_hi:[0,1,1]
	v_pk_fma_f32 v[14:15], v[106:107], v[80:81], v[14:15] op_sel_hi:[0,1,1]
	s_waitcnt lgkmcnt(1)
	v_fmac_f32_e32 v21, v106, v54
	v_pk_fma_f32 v[12:13], v[98:99], v[30:31], v[12:13] op_sel_hi:[0,1,1]
	v_pk_fma_f32 v[14:15], v[98:99], v[46:47], v[14:15] op_sel_hi:[0,1,1]
	v_fmac_f32_e32 v21, v98, v55
	v_pk_fma_f32 v[12:13], v[100:101], v[22:23], v[12:13] op_sel_hi:[0,1,1]
	v_pk_fma_f32 v[14:15], v[100:101], v[38:39], v[14:15] op_sel_hi:[0,1,1]
	v_fmac_f32_e32 v21, v100, v56
	v_pk_fma_f32 v[12:13], v[102:103], v[32:33], v[12:13] op_sel_hi:[0,1,1]
	v_pk_fma_f32 v[14:15], v[102:103], v[48:49], v[14:15] op_sel_hi:[0,1,1]
	v_fmac_f32_e32 v21, v102, v57
	v_pk_fma_f32 v[12:13], v[104:105], v[24:25], v[12:13] op_sel_hi:[0,1,1]
	v_pk_fma_f32 v[14:15], v[104:105], v[40:41], v[14:15] op_sel_hi:[0,1,1]
	s_waitcnt lgkmcnt(0)
	v_fmac_f32_e32 v21, v104, v58
	s_waitcnt vmcnt(10)
	v_pk_fma_f32 v[12:13], v[108:109], v[34:35], v[12:13] op_sel_hi:[0,1,1]
	v_pk_fma_f32 v[14:15], v[108:109], v[50:51], v[14:15] op_sel_hi:[0,1,1]
	v_fmac_f32_e32 v21, v108, v59
	s_waitcnt vmcnt(9)
	v_pk_fma_f32 v[12:13], v[110:111], v[26:27], v[12:13] op_sel_hi:[0,1,1]
	v_pk_fma_f32 v[14:15], v[110:111], v[42:43], v[14:15] op_sel_hi:[0,1,1]
	v_fmac_f32_e32 v21, v110, v60
	s_waitcnt vmcnt(8)
	v_pk_fma_f32 v[12:13], v[112:113], v[36:37], v[12:13] op_sel_hi:[0,1,1]
	v_pk_fma_f32 v[14:15], v[112:113], v[52:53], v[14:15] op_sel_hi:[0,1,1]
	v_fmac_f32_e32 v21, v112, v61
	s_add_i32 s46, s2, s0
	v_mov_b32_e32 v50, s46
	s_add_i32 s49, s46, 0x10800
	s_add_i32 s50, s46, 0x10810
	ds_read_b128 v[22:25], v50 offset:2048
	ds_read_b128 v[26:29], v50 offset:2064
	v_mov_b32_e32 v54, s49
	ds_read_b128 v[30:33], v50 offset:18432
	ds_read_b128 v[34:37], v50 offset:18448
	ds_read_b128 v[38:41], v50 offset:34816
	ds_read_b128 v[42:45], v50 offset:34832
	ds_read_b128 v[46:49], v50 offset:51200
	ds_read_b128 v[50:53], v50 offset:51216
	v_mov_b32_e32 v58, s50
	ds_read_b128 v[54:57], v54
	ds_read_b128 v[58:61], v58
	s_waitcnt lgkmcnt(9)
	v_mov_b32_e32 v78, v22
	s_waitcnt lgkmcnt(7)
	v_mov_b32_e32 v79, v30
	s_waitcnt lgkmcnt(5)
	v_mov_b32_e32 v80, v38
	s_waitcnt lgkmcnt(3)
	v_mov_b32_e32 v81, v46
	v_mov_b32_e32 v30, v23
	v_mov_b32_e32 v46, v39
	v_mov_b32_e32 v22, v24
	v_mov_b32_e32 v23, v32
	v_mov_b32_e32 v38, v40
	v_mov_b32_e32 v39, v48
	v_mov_b32_e32 v32, v25
	v_mov_b32_e32 v48, v41
	v_mov_b32_e32 v24, v26
	v_mov_b32_e32 v25, v34
	v_mov_b32_e32 v40, v42
	s_waitcnt lgkmcnt(2)
	v_mov_b32_e32 v41, v50
	v_mov_b32_e32 v34, v27
	v_mov_b32_e32 v50, v43
	v_mov_b32_e32 v26, v28
	v_mov_b32_e32 v27, v36
	v_mov_b32_e32 v42, v44
	v_mov_b32_e32 v43, v52
	s_add_i32 s0, s0, 32
	s_mov_b64 s[46:47], 0x60000
	v_mov_b32_e32 v36, v29
	v_mov_b32_e32 v52, v45
	v_lshl_add_u64 v[10:11], v[10:11], 0, s[46:47]
	s_cmp_eq_u32 s0, 0
	s_waitcnt vmcnt(3)
	v_pk_fma_f32 v[12:13], v[122:123], v[78:79], v[12:13] op_sel_hi:[0,1,1]
	v_pk_fma_f32 v[14:15], v[122:123], v[80:81], v[14:15] op_sel_hi:[0,1,1]
	s_waitcnt lgkmcnt(1)
	v_fmac_f32_e32 v21, v122, v54
	v_pk_fma_f32 v[12:13], v[114:115], v[30:31], v[12:13] op_sel_hi:[0,1,1]
	v_pk_fma_f32 v[14:15], v[114:115], v[46:47], v[14:15] op_sel_hi:[0,1,1]
	v_fmac_f32_e32 v21, v114, v55
	v_pk_fma_f32 v[12:13], v[116:117], v[22:23], v[12:13] op_sel_hi:[0,1,1]
	v_pk_fma_f32 v[14:15], v[116:117], v[38:39], v[14:15] op_sel_hi:[0,1,1]
	v_fmac_f32_e32 v21, v116, v56
	v_pk_fma_f32 v[12:13], v[118:119], v[32:33], v[12:13] op_sel_hi:[0,1,1]
	v_pk_fma_f32 v[14:15], v[118:119], v[48:49], v[14:15] op_sel_hi:[0,1,1]
	v_fmac_f32_e32 v21, v118, v57
	v_pk_fma_f32 v[12:13], v[120:121], v[24:25], v[12:13] op_sel_hi:[0,1,1]
	v_pk_fma_f32 v[14:15], v[120:121], v[40:41], v[14:15] op_sel_hi:[0,1,1]
	s_waitcnt lgkmcnt(0)
	v_fmac_f32_e32 v21, v120, v58
	s_waitcnt vmcnt(2)
	v_pk_fma_f32 v[12:13], v[124:125], v[34:35], v[12:13] op_sel_hi:[0,1,1]
	v_pk_fma_f32 v[14:15], v[124:125], v[50:51], v[14:15] op_sel_hi:[0,1,1]
	v_fmac_f32_e32 v21, v124, v59
	s_waitcnt vmcnt(1)
	v_pk_fma_f32 v[12:13], v[126:127], v[26:27], v[12:13] op_sel_hi:[0,1,1]
	v_pk_fma_f32 v[14:15], v[126:127], v[42:43], v[14:15] op_sel_hi:[0,1,1]
	v_fmac_f32_e32 v21, v126, v60
	s_waitcnt vmcnt(0)
	v_pk_fma_f32 v[12:13], v[128:129], v[36:37], v[12:13] op_sel_hi:[0,1,1]
	v_pk_fma_f32 v[14:15], v[128:129], v[52:53], v[14:15] op_sel_hi:[0,1,1]
	v_fmac_f32_e32 v21, v128, v61
	s_cbranch_scc0 .LBB0_34
	ds_write2st64_b32 v17, v12, v13 offset1:1
	ds_write2st64_b32 v17, v14, v15 offset0:2 offset1:3
	ds_write_b32 v17, v21 offset:1024
	s_waitcnt lgkmcnt(0)
	s_barrier
	s_and_saveexec_b64 s[46:47], s[40:41]
	s_cbranch_execz .LBB0_16
	s_lshl_b32 s50, s56, 6
	v_add_u32_e32 v10, s50, v2
	v_ashrrev_i32_e32 v11, 31, v10
	v_lshl_add_u64 v[10:11], v[10:11], 2, s[12:13]
	global_load_dword v21, v[10:11], off nt
	ds_read2st64_b32 v[10:11], v20 offset1:5
	ds_read2st64_b32 v[12:13], v20 offset0:10 offset1:15
	ds_read2st64_b32 v[14:15], v20 offset0:20 offset1:25
	ds_read2st64_b32 v[22:23], v20 offset0:30 offset1:35
	s_ashr_i32 s51, s50, 31
	s_waitcnt lgkmcnt(3)
	v_add_f32_e32 v10, 0, v10
	v_add_f32_e32 v10, v10, v11
	s_waitcnt lgkmcnt(2)
	v_add_f32_e32 v10, v10, v12
	v_add_f32_e32 v10, v10, v13
	s_waitcnt lgkmcnt(1)
	v_add_f32_e32 v10, v10, v14
	v_add_f32_e32 v10, v10, v15
	s_waitcnt lgkmcnt(0)
	v_add_f32_e32 v10, v10, v22
	v_add_f32_e32 v10, v10, v23
	s_waitcnt vmcnt(0)
	v_add_f32_e32 v12, v10, v21
	v_lshl_add_u64 v[10:11], s[50:51], 2, v[4:5]
	global_store_dword v[10:11], v12, off
	s_branch .LBB0_16

.Lpb_next:
	s_add_i32 s65, s65, s3
	s_cmpk_lt_i32 s65, 0x440
	s_cbranch_scc1 .Lpb_loop
	s_branch .LBB0_178
	s_nop 0
	s_nop 0
	s_nop 0
	s_nop 0
	s_nop 0
	s_nop 0
	s_nop 0
	s_nop 0
	s_nop 0
	s_nop 0
	s_nop 0
	s_nop 0
	s_nop 0
	s_nop 0
	s_nop 0
	s_nop 0
	s_nop 0
	s_nop 0
	s_nop 0
	s_nop 0
	s_nop 0
	s_branch .LBB0_178
	s_nop 0
	s_nop 0
	s_nop 0
	s_nop 0
	s_nop 0
	s_nop 0
	s_nop 0
	s_nop 0
	s_nop 0
	s_nop 0
	s_nop 0
	s_nop 0
	s_nop 0
	s_nop 0
	s_nop 0
.LBB0_178:
	v_readlane_b32 s0, v255, 10
	v_readlane_b32 s60, v255, 0
	s_add_i32 s0, s0, 2
	v_readlane_b32 s63, v255, 3
	v_readlane_b32 s62, v255, 2
	s_cmp_ge_i32 s0, s63
	s_barrier
	v_readlane_b32 s61, v255, 1
	s_cbranch_scc1 .LBB0_190
	s_waitcnt vmcnt(0)
	s_barrier
	s_mov_b64 s[4:5], exec
	v_readlane_b32 s6, v254, 56
	v_readlane_b32 s7, v254, 57
	v_readlane_b32 s60, v255, 6
	s_and_b64 s[6:7], s[4:5], s[6:7]
	v_readlane_b32 s61, v255, 7
	s_mov_b64 exec, s[6:7]
	s_cbranch_execz .LBB0_228
	v_readlane_b32 s2, v253, 2
	s_waitcnt vmcnt(0) expcnt(0) lgkmcnt(0)
	s_nop 0
	v_mov_b32_e32 v2, s2
	ds_read_b32 v4, v2
	ds_read_b32 v2, v2 offset:4
	s_waitcnt lgkmcnt(1)
	v_cmp_ne_u32_e32 vcc, 0, v4
	s_cbranch_vccnz .LBB0_196
	v_readlane_b32 s8, v253, 0
	v_readlane_b32 s9, v253, 1
	s_load_dwordx2 s[6:7], s[8:9], 0x4
	s_mov_b32 s12, 1
	s_waitcnt lgkmcnt(0)
	s_mul_i32 s2, s6, s3
	s_mul_i32 s2, s2, s7
	s_branch .LBB0_183
